# P2 swiglu epilogue hand-written with packed f32 ops (same operation order)
# speedup vs baseline: 1.0088x; 1.0021x over previous
; __device__ __forceinline__ u32x4 pack8(const f32x4 a, const f32x4 b) { u32x4 w; w.x = cvt_pk_bf16(a[0], a[1]); w.y = cvt_pk_bf16(a[2], a[3]); w.z = cvt_pk_bf16(b[0], b[1]); w.w = cvt_pk_bf16(b[2], b[3]); return w; }
; __device__ __forceinline__ float sigm(float v) { return __builtin_amdgcn_rcpf(1.f + __expf(-v)); }
; #define EPI_ROWS _Pragma("unroll") for (int ai = 0; ai < 2; ++ai) _Pragma("unroll") for (int m = 0; m < 4; ++m)
;     __device__ __forceinline__ void operator()(const f32x4 (&acc)[2][2][4][2], const Unit& u, int wr, int wc, int fr, int fq) const {
;     ...
;         EPI_ROWS { const int row = EPI_ROW;
;             f32x4 a0 = acc[ai][0][m][0], a1 = acc[ai][0][m][1], b0 = acc[ai][1][m][0], b1 = acc[ai][1][m][1];
;             if (NORM) { const float rs = rsv[ai][m]; a0 = a0 * rs + ba0; a1 = a1 * rs + ba1; b0 = b0 * rs + bb0; b1 = b1 * rs + bb1; }
;             f32x4 o0, o1;
; #pragma unroll
;             for (int i = 0; i < 4; ++i) { o0[i] = a0[i] * sigm(a0[i]) * b0[i]; o1[i] = a1[i] * sigm(a1[i]) * b1[i]; }
;             *(u32x4*)(act + (size_t)(row >> 1) * (2 * DFF) + (u.pn * 4 + wc) * 64 + (row & 1) * 32 + fq * 8) = pack8(o0, o1); }
.LBB0_211:
	v_mov_b32_e32 v154, 0xbfb8aa3b
	v_mov_b32_e32 v155, 0xbfb8aa3b
	v_lshrrev_b32_e32 v180, 1, v1
	v_mul_u32_u24_e32 v180, 0x2c00, v180
	v_and_b32_e32 v181, 1, v1
	v_lshl_add_u32 v180, v181, 6, v180
	v_lshl_add_u32 v180, v148, 4, v180
	s_lshl_b32 s13, s20, 8
	s_add_i32 s13, s13, s41
	s_lshr_b32 s13, s13, 1
	s_mul_i32 s13, s13, 0x2c00
	s_lshl_b32 s22, s21, 8
	s_or_b32 s22, s22, s45
	s_lshl_b32 s22, s22, 1
	s_add_u32 s13, s13, s22
	s_add_u32 s22, s6, s13
	s_addc_u32 s23, s7, 0
	v_pk_mul_f32 v[156:157], v[154:155], v[126:127]
	v_pk_mul_f32 v[158:159], v[154:155], v[128:129]
	v_pk_mul_f32 v[160:161], v[154:155], v[122:123]
	v_pk_mul_f32 v[162:163], v[154:155], v[124:125]
	v_exp_f32_e32 v156, v156
	v_exp_f32_e32 v157, v157
	v_exp_f32_e32 v158, v158
	v_exp_f32_e32 v159, v159
	v_exp_f32_e32 v160, v160
	v_exp_f32_e32 v161, v161
	v_exp_f32_e32 v162, v162
	v_exp_f32_e32 v163, v163
	v_pk_add_f32 v[156:157], v[156:157], 1.0 op_sel_hi:[1,0]
	v_pk_add_f32 v[158:159], v[158:159], 1.0 op_sel_hi:[1,0]
	v_pk_add_f32 v[160:161], v[160:161], 1.0 op_sel_hi:[1,0]
	v_pk_add_f32 v[162:163], v[162:163], 1.0 op_sel_hi:[1,0]
	v_rcp_f32_e32 v156, v156
	v_rcp_f32_e32 v157, v157
	v_rcp_f32_e32 v158, v158
	v_rcp_f32_e32 v159, v159
	v_rcp_f32_e32 v160, v160
	v_rcp_f32_e32 v161, v161
	v_rcp_f32_e32 v162, v162
	v_rcp_f32_e32 v163, v163
	v_pk_mul_f32 v[156:157], v[126:127], v[156:157]
	v_pk_mul_f32 v[158:159], v[128:129], v[158:159]
	v_pk_mul_f32 v[160:161], v[122:123], v[160:161]
	v_pk_mul_f32 v[162:163], v[124:125], v[162:163]
	v_pk_mul_f32 v[156:157], v[156:157], v[118:119]
	v_pk_mul_f32 v[158:159], v[158:159], v[120:121]
	v_pk_mul_f32 v[160:161], v[160:161], v[114:115]
	v_pk_mul_f32 v[162:163], v[162:163], v[116:117]
	v_cvt_pk_bf16_f32 v172, v156, v157
	v_cvt_pk_bf16_f32 v173, v158, v159
	v_cvt_pk_bf16_f32 v174, v160, v161
	v_cvt_pk_bf16_f32 v175, v162, v163
	global_store_dwordx4 v180, v[172:175], s[22:23]
	s_add_u32 s22, s22, 0x16000
	s_addc_u32 s23, s23, 0
	v_pk_mul_f32 v[164:165], v[154:155], v[110:111]
	v_pk_mul_f32 v[166:167], v[154:155], v[112:113]
	v_pk_mul_f32 v[168:169], v[154:155], v[106:107]
	v_pk_mul_f32 v[170:171], v[154:155], v[108:109]
	v_exp_f32_e32 v164, v164
	v_exp_f32_e32 v165, v165
	v_exp_f32_e32 v166, v166
	v_exp_f32_e32 v167, v167
	v_exp_f32_e32 v168, v168
	v_exp_f32_e32 v169, v169
	v_exp_f32_e32 v170, v170
	v_exp_f32_e32 v171, v171
	v_pk_add_f32 v[164:165], v[164:165], 1.0 op_sel_hi:[1,0]
	v_pk_add_f32 v[166:167], v[166:167], 1.0 op_sel_hi:[1,0]
	v_pk_add_f32 v[168:169], v[168:169], 1.0 op_sel_hi:[1,0]
	v_pk_add_f32 v[170:171], v[170:171], 1.0 op_sel_hi:[1,0]
	v_rcp_f32_e32 v164, v164
	v_rcp_f32_e32 v165, v165
	v_rcp_f32_e32 v166, v166
	v_rcp_f32_e32 v167, v167
	v_rcp_f32_e32 v168, v168
	v_rcp_f32_e32 v169, v169
	v_rcp_f32_e32 v170, v170
	v_rcp_f32_e32 v171, v171
	v_pk_mul_f32 v[164:165], v[110:111], v[164:165]
	v_pk_mul_f32 v[166:167], v[112:113], v[166:167]
	v_pk_mul_f32 v[168:169], v[106:107], v[168:169]
	v_pk_mul_f32 v[170:171], v[108:109], v[170:171]
	v_pk_mul_f32 v[164:165], v[164:165], v[102:103]
	v_pk_mul_f32 v[166:167], v[166:167], v[104:105]
	v_pk_mul_f32 v[168:169], v[168:169], v[98:99]
	v_pk_mul_f32 v[170:171], v[170:171], v[100:101]
	v_cvt_pk_bf16_f32 v176, v164, v165
	v_cvt_pk_bf16_f32 v177, v166, v167
	v_cvt_pk_bf16_f32 v178, v168, v169
	v_cvt_pk_bf16_f32 v179, v170, v171
	global_store_dwordx4 v180, v[176:179], s[22:23]
	s_add_u32 s22, s22, 0x16000
	s_addc_u32 s23, s23, 0
	v_pk_mul_f32 v[156:157], v[154:155], v[94:95]
	v_pk_mul_f32 v[158:159], v[154:155], v[96:97]
	v_pk_mul_f32 v[160:161], v[154:155], v[90:91]
	v_pk_mul_f32 v[162:163], v[154:155], v[92:93]
	v_exp_f32_e32 v156, v156
	v_exp_f32_e32 v157, v157
	v_exp_f32_e32 v158, v158
	v_exp_f32_e32 v159, v159
	v_exp_f32_e32 v160, v160
	v_exp_f32_e32 v161, v161
	v_exp_f32_e32 v162, v162
	v_exp_f32_e32 v163, v163
	v_pk_add_f32 v[156:157], v[156:157], 1.0 op_sel_hi:[1,0]
	v_pk_add_f32 v[158:159], v[158:159], 1.0 op_sel_hi:[1,0]
	v_pk_add_f32 v[160:161], v[160:161], 1.0 op_sel_hi:[1,0]
	v_pk_add_f32 v[162:163], v[162:163], 1.0 op_sel_hi:[1,0]
	v_rcp_f32_e32 v156, v156
	v_rcp_f32_e32 v157, v157
	v_rcp_f32_e32 v158, v158
	v_rcp_f32_e32 v159, v159
	v_rcp_f32_e32 v160, v160
	v_rcp_f32_e32 v161, v161
	v_rcp_f32_e32 v162, v162
	v_rcp_f32_e32 v163, v163
	v_pk_mul_f32 v[156:157], v[94:95], v[156:157]
	v_pk_mul_f32 v[158:159], v[96:97], v[158:159]
	v_pk_mul_f32 v[160:161], v[90:91], v[160:161]
	v_pk_mul_f32 v[162:163], v[92:93], v[162:163]
	v_pk_mul_f32 v[156:157], v[156:157], v[86:87]
	v_pk_mul_f32 v[158:159], v[158:159], v[88:89]
	v_pk_mul_f32 v[160:161], v[160:161], v[82:83]
	v_pk_mul_f32 v[162:163], v[162:163], v[84:85]
	v_cvt_pk_bf16_f32 v172, v156, v157
	v_cvt_pk_bf16_f32 v173, v158, v159
	v_cvt_pk_bf16_f32 v174, v160, v161
	v_cvt_pk_bf16_f32 v175, v162, v163
	global_store_dwordx4 v180, v[172:175], s[22:23]
	s_add_u32 s22, s22, 0x16000
	s_addc_u32 s23, s23, 0
	v_pk_mul_f32 v[164:165], v[154:155], v[78:79]
	v_pk_mul_f32 v[166:167], v[154:155], v[80:81]
	v_pk_mul_f32 v[168:169], v[154:155], v[74:75]
	v_pk_mul_f32 v[170:171], v[154:155], v[76:77]
	v_exp_f32_e32 v164, v164
	v_exp_f32_e32 v165, v165
	v_exp_f32_e32 v166, v166
	v_exp_f32_e32 v167, v167
	v_exp_f32_e32 v168, v168
	v_exp_f32_e32 v169, v169
	v_exp_f32_e32 v170, v170
	v_exp_f32_e32 v171, v171
	v_pk_add_f32 v[164:165], v[164:165], 1.0 op_sel_hi:[1,0]
	v_pk_add_f32 v[166:167], v[166:167], 1.0 op_sel_hi:[1,0]
	v_pk_add_f32 v[168:169], v[168:169], 1.0 op_sel_hi:[1,0]
	v_pk_add_f32 v[170:171], v[170:171], 1.0 op_sel_hi:[1,0]
	v_rcp_f32_e32 v164, v164
	v_rcp_f32_e32 v165, v165
	v_rcp_f32_e32 v166, v166
	v_rcp_f32_e32 v167, v167
; __device__ __forceinline__ u32x4 pack8(const f32x4 a, const f32x4 b) { u32x4 w; w.x = cvt_pk_bf16(a[0], a[1]); w.y = cvt_pk_bf16(a[2], a[3]); w.z = cvt_pk_bf16(b[0], b[1]); w.w = cvt_pk_bf16(b[2], b[3]); return w; }
; __device__ __forceinline__ float sigm(float v) { return __builtin_amdgcn_rcpf(1.f + __expf(-v)); }
; #define EPI_ROWS _Pragma("unroll") for (int ai = 0; ai < 2; ++ai) _Pragma("unroll") for (int m = 0; m < 4; ++m)
;     __device__ __forceinline__ void operator()(const f32x4 (&acc)[2][2][4][2], const Unit& u, int wr, int wc, int fr, int fq) const {
;     ...
;         EPI_ROWS { const int row = EPI_ROW;
;             f32x4 a0 = acc[ai][0][m][0], a1 = acc[ai][0][m][1], b0 = acc[ai][1][m][0], b1 = acc[ai][1][m][1];
;             if (NORM) { const float rs = rsv[ai][m]; a0 = a0 * rs + ba0; a1 = a1 * rs + ba1; b0 = b0 * rs + bb0; b1 = b1 * rs + bb1; }
;             f32x4 o0, o1;
; #pragma unroll
;             for (int i = 0; i < 4; ++i) { o0[i] = a0[i] * sigm(a0[i]) * b0[i]; o1[i] = a1[i] * sigm(a1[i]) * b1[i]; }
;             *(u32x4*)(act + (size_t)(row >> 1) * (2 * DFF) + (u.pn * 4 + wc) * 64 + (row & 1) * 32 + fq * 8) = pack8(o0, o1); }
	v_rcp_f32_e32 v168, v168
	v_rcp_f32_e32 v169, v169
	v_rcp_f32_e32 v170, v170
	v_rcp_f32_e32 v171, v171
	v_pk_mul_f32 v[164:165], v[78:79], v[164:165]
	v_pk_mul_f32 v[166:167], v[80:81], v[166:167]
	v_pk_mul_f32 v[168:169], v[74:75], v[168:169]
	v_pk_mul_f32 v[170:171], v[76:77], v[170:171]
	v_pk_mul_f32 v[164:165], v[164:165], v[70:71]
	v_pk_mul_f32 v[166:167], v[166:167], v[72:73]
	v_pk_mul_f32 v[168:169], v[168:169], v[66:67]
	v_pk_mul_f32 v[170:171], v[170:171], v[68:69]
	v_cvt_pk_bf16_f32 v176, v164, v165
	v_cvt_pk_bf16_f32 v177, v166, v167
	v_cvt_pk_bf16_f32 v178, v168, v169
	v_cvt_pk_bf16_f32 v179, v170, v171
	global_store_dwordx4 v180, v[176:179], s[22:23]
	s_add_u32 s22, s22, 0x6e000
	s_addc_u32 s23, s23, 0
	v_pk_mul_f32 v[156:157], v[154:155], v[62:63]
	v_pk_mul_f32 v[158:159], v[154:155], v[64:65]
	v_pk_mul_f32 v[160:161], v[154:155], v[58:59]
	v_pk_mul_f32 v[162:163], v[154:155], v[60:61]
	v_exp_f32_e32 v156, v156
	v_exp_f32_e32 v157, v157
	v_exp_f32_e32 v158, v158
	v_exp_f32_e32 v159, v159
	v_exp_f32_e32 v160, v160
	v_exp_f32_e32 v161, v161
	v_exp_f32_e32 v162, v162
	v_exp_f32_e32 v163, v163
	v_pk_add_f32 v[156:157], v[156:157], 1.0 op_sel_hi:[1,0]
	v_pk_add_f32 v[158:159], v[158:159], 1.0 op_sel_hi:[1,0]
	v_pk_add_f32 v[160:161], v[160:161], 1.0 op_sel_hi:[1,0]
	v_pk_add_f32 v[162:163], v[162:163], 1.0 op_sel_hi:[1,0]
	v_rcp_f32_e32 v156, v156
	v_rcp_f32_e32 v157, v157
	v_rcp_f32_e32 v158, v158
	v_rcp_f32_e32 v159, v159
	v_rcp_f32_e32 v160, v160
	v_rcp_f32_e32 v161, v161
	v_rcp_f32_e32 v162, v162
	v_rcp_f32_e32 v163, v163
	v_pk_mul_f32 v[156:157], v[62:63], v[156:157]
	v_pk_mul_f32 v[158:159], v[64:65], v[158:159]
	v_pk_mul_f32 v[160:161], v[58:59], v[160:161]
	v_pk_mul_f32 v[162:163], v[60:61], v[162:163]
	v_pk_mul_f32 v[156:157], v[156:157], v[54:55]
	v_pk_mul_f32 v[158:159], v[158:159], v[56:57]
	v_pk_mul_f32 v[160:161], v[160:161], v[50:51]
	v_pk_mul_f32 v[162:163], v[162:163], v[52:53]
	v_cvt_pk_bf16_f32 v172, v156, v157
	v_cvt_pk_bf16_f32 v173, v158, v159
	v_cvt_pk_bf16_f32 v174, v160, v161
	v_cvt_pk_bf16_f32 v175, v162, v163
	global_store_dwordx4 v180, v[172:175], s[22:23]
	s_add_u32 s22, s22, 0x16000
	s_addc_u32 s23, s23, 0
	v_pk_mul_f32 v[164:165], v[154:155], v[46:47]
	v_pk_mul_f32 v[166:167], v[154:155], v[48:49]
	v_pk_mul_f32 v[168:169], v[154:155], v[42:43]
	v_pk_mul_f32 v[170:171], v[154:155], v[44:45]
	v_exp_f32_e32 v164, v164
	v_exp_f32_e32 v165, v165
	v_exp_f32_e32 v166, v166
	v_exp_f32_e32 v167, v167
	v_exp_f32_e32 v168, v168
	v_exp_f32_e32 v169, v169
	v_exp_f32_e32 v170, v170
	v_exp_f32_e32 v171, v171
	v_pk_add_f32 v[164:165], v[164:165], 1.0 op_sel_hi:[1,0]
	v_pk_add_f32 v[166:167], v[166:167], 1.0 op_sel_hi:[1,0]
	v_pk_add_f32 v[168:169], v[168:169], 1.0 op_sel_hi:[1,0]
	v_pk_add_f32 v[170:171], v[170:171], 1.0 op_sel_hi:[1,0]
	v_rcp_f32_e32 v164, v164
	v_rcp_f32_e32 v165, v165
	v_rcp_f32_e32 v166, v166
	v_rcp_f32_e32 v167, v167
	v_rcp_f32_e32 v168, v168
	v_rcp_f32_e32 v169, v169
	v_rcp_f32_e32 v170, v170
	v_rcp_f32_e32 v171, v171
	v_pk_mul_f32 v[164:165], v[46:47], v[164:165]
	v_pk_mul_f32 v[166:167], v[48:49], v[166:167]
	v_pk_mul_f32 v[168:169], v[42:43], v[168:169]
	v_pk_mul_f32 v[170:171], v[44:45], v[170:171]
	v_pk_mul_f32 v[164:165], v[164:165], v[38:39]
	v_pk_mul_f32 v[166:167], v[166:167], v[40:41]
	v_pk_mul_f32 v[168:169], v[168:169], v[34:35]
	v_pk_mul_f32 v[170:171], v[170:171], v[36:37]
	v_cvt_pk_bf16_f32 v176, v164, v165
	v_cvt_pk_bf16_f32 v177, v166, v167
	v_cvt_pk_bf16_f32 v178, v168, v169
	v_cvt_pk_bf16_f32 v179, v170, v171
	global_store_dwordx4 v180, v[176:179], s[22:23]
	s_add_u32 s22, s22, 0x16000
	s_addc_u32 s23, s23, 0
	v_pk_mul_f32 v[156:157], v[154:155], v[30:31]
	v_pk_mul_f32 v[158:159], v[154:155], v[32:33]
	v_pk_mul_f32 v[160:161], v[154:155], v[26:27]
	v_pk_mul_f32 v[162:163], v[154:155], v[28:29]
	v_exp_f32_e32 v156, v156
	v_exp_f32_e32 v157, v157
	v_exp_f32_e32 v158, v158
	v_exp_f32_e32 v159, v159
	v_exp_f32_e32 v160, v160
	v_exp_f32_e32 v161, v161
	v_exp_f32_e32 v162, v162
	v_exp_f32_e32 v163, v163
	v_pk_add_f32 v[156:157], v[156:157], 1.0 op_sel_hi:[1,0]
	v_pk_add_f32 v[158:159], v[158:159], 1.0 op_sel_hi:[1,0]
	v_pk_add_f32 v[160:161], v[160:161], 1.0 op_sel_hi:[1,0]
	v_pk_add_f32 v[162:163], v[162:163], 1.0 op_sel_hi:[1,0]
	v_rcp_f32_e32 v156, v156
	v_rcp_f32_e32 v157, v157
	v_rcp_f32_e32 v158, v158
	v_rcp_f32_e32 v159, v159
	v_rcp_f32_e32 v160, v160
	v_rcp_f32_e32 v161, v161
	v_rcp_f32_e32 v162, v162
	v_rcp_f32_e32 v163, v163
	v_pk_mul_f32 v[156:157], v[30:31], v[156:157]
	v_pk_mul_f32 v[158:159], v[32:33], v[158:159]
	v_pk_mul_f32 v[160:161], v[26:27], v[160:161]
	v_pk_mul_f32 v[162:163], v[28:29], v[162:163]
	v_pk_mul_f32 v[156:157], v[156:157], v[22:23]
	v_pk_mul_f32 v[158:159], v[158:159], v[24:25]
	v_pk_mul_f32 v[160:161], v[160:161], v[18:19]
	v_pk_mul_f32 v[162:163], v[162:163], v[20:21]
	v_cvt_pk_bf16_f32 v172, v156, v157
	v_cvt_pk_bf16_f32 v173, v158, v159
	v_cvt_pk_bf16_f32 v174, v160, v161
	v_cvt_pk_bf16_f32 v175, v162, v163
	global_store_dwordx4 v180, v[172:175], s[22:23]
	s_add_u32 s22, s22, 0x16000
	s_addc_u32 s23, s23, 0
	v_pk_mul_f32 v[164:165], v[154:155], v[14:15]
	v_pk_mul_f32 v[166:167], v[154:155], v[16:17]
	v_pk_mul_f32 v[168:169], v[154:155], v[10:11]
	v_pk_mul_f32 v[170:171], v[154:155], v[12:13]
	v_exp_f32_e32 v164, v164
	v_exp_f32_e32 v165, v165
	v_exp_f32_e32 v166, v166
	v_exp_f32_e32 v167, v167
	v_exp_f32_e32 v168, v168
	v_exp_f32_e32 v169, v169
	v_exp_f32_e32 v170, v170
	v_exp_f32_e32 v171, v171
	v_pk_add_f32 v[164:165], v[164:165], 1.0 op_sel_hi:[1,0]
	v_pk_add_f32 v[166:167], v[166:167], 1.0 op_sel_hi:[1,0]
	v_pk_add_f32 v[168:169], v[168:169], 1.0 op_sel_hi:[1,0]
	v_pk_add_f32 v[170:171], v[170:171], 1.0 op_sel_hi:[1,0]
	v_rcp_f32_e32 v164, v164
	v_rcp_f32_e32 v165, v165
	v_rcp_f32_e32 v166, v166
	v_rcp_f32_e32 v167, v167
	v_rcp_f32_e32 v168, v168
	v_rcp_f32_e32 v169, v169
	v_rcp_f32_e32 v170, v170
	v_rcp_f32_e32 v171, v171
	v_pk_mul_f32 v[164:165], v[14:15], v[164:165]
	v_pk_mul_f32 v[166:167], v[16:17], v[166:167]
	v_pk_mul_f32 v[168:169], v[10:11], v[168:169]
	v_pk_mul_f32 v[170:171], v[12:13], v[170:171]
	v_pk_mul_f32 v[164:165], v[164:165], v[6:7]
	v_pk_mul_f32 v[166:167], v[166:167], v[8:9]
	v_pk_mul_f32 v[168:169], v[168:169], v[2:3]
	v_pk_mul_f32 v[170:171], v[170:171], v[4:5]
	v_cvt_pk_bf16_f32 v176, v164, v165
	v_cvt_pk_bf16_f32 v177, v166, v167
	v_cvt_pk_bf16_f32 v178, v168, v169
	v_cvt_pk_bf16_f32 v179, v170, v171
	s_andn2_b64 vcc, exec, s[0:1]
	s_mov_b64 s[0:1], -1
	global_store_dwordx4 v180, v[176:179], s[22:23]
	s_cbranch_vccnz .LBB0_204
	s_andn2_b64 vcc, exec, s[4:5]
	s_cbranch_vccnz .LBB0_203
	s_barrier
	s_branch .LBB0_203
